# mixers units remapped batch->XCD so whole layer is XCD-local; fast barrier also on in-proj->mixers->y seams
# speedup vs baseline: 1.0504x; 1.0093x over previous
.LBB0_440:
	s_waitcnt vmcnt(0)
	v_mov_b32_e32 v1, v218
	s_waitcnt lgkmcnt(0)
	s_barrier
	s_nop 0
	v_cmp_eq_u32_e32 vcc, 0, v1
	s_and_saveexec_b64 s[2:3], vcc
	s_mov_b32 s1, 0x7f807f81
	s_movk_i32 s50, 0x5b
	s_mov_b32 s51, 0xf800000
	s_mov_b32 s52, 0x3fb8aa3b
	s_cbranch_execz .LBB0_492
	v_readlane_b32 s100, v255, 40
	s_nop 3
	s_cmp_eq_u32 s100, 0
	s_cbranch_scc1 .Lfb_slow_3
	v_readlane_b32 s100, v255, 41
	v_readlane_b32 s101, v255, 42
	v_mov_b32_e32 v2, 0
	v_mov_b32_e32 v3, 1
	v_mov_b32_e32 v4, 1
	s_nop 2
	global_atomic_add v3, v2, v3, s[100:101] sc0
	s_waitcnt vmcnt(0)
	v_readfirstlane_b32 vcc_hi, v3
	s_nop 3
	s_lshr_b32 vcc_lo, vcc_hi, 5
	s_add_i32 vcc_hi, vcc_hi, 1
	s_and_b32 vcc_hi, vcc_hi, 31
	s_cmp_lg_u32 vcc_hi, 0
	s_cbranch_scc1 .Lfb_spin_3
	global_atomic_add v2, v4, s[100:101] offset:128
	s_branch .Lfb_done_3

.LBB0_527:
	v_readlane_b32 s100, v255, 40
	s_and_b32 s18, s20, 7
	s_lshl_b32 s18, s18, 6
	s_lshr_b32 s19, s20, 3
	s_or_b32 s18, s18, s19
	s_cmp_lg_u32 s100, 0
	s_cselect_b32 s18, s18, s20
	s_lshl_b32 s18, s18, 6
	s_and_b32 s21, s18, 0xfc0
	s_add_i32 s21, s21, -15
	v_add_u32_e32 v3, s21, v43
	v_cmp_gt_u32_e32 vcc, s33, v3
	s_and_b32 s19, s18, 0xfffff000
	s_and_b64 s[28:29], s[2:3], vcc
	v_mov_b32_e32 v2, 0
	v_mov_b32_e32 v6, 0
	v_mov_b32_e32 v7, 0
	v_mov_b32_e32 v8, 0
	v_mov_b32_e32 v9, 0
	s_and_saveexec_b64 s[14:15], s[28:29]
	s_cbranch_execz .LBB0_529
	v_or_b32_e32 v4, s19, v3
	v_ashrrev_i32_e32 v5, 31, v4
	v_lshlrev_b64 v[4:5], 11, v[4:5]
	v_lshl_add_u64 v[4:5], v[46:47], 0, v[4:5]
	global_load_dwordx4 v[6:9], v[4:5], off

.LBB0_557:
	v_readlane_b32 s100, v255, 40
	s_bfe_u32 s101, s15, 0x30003
	s_lshl_b32 s101, s101, 9
	s_bfe_u32 s2, s15, 0x1000b
	s_lshl_b32 s2, s2, 8
	s_or_b32 s101, s101, s2
	s_bfe_u32 s2, s15, 0x50006
	s_lshl_b32 s2, s2, 3
	s_or_b32 s101, s101, s2
	s_and_b32 s2, s15, 7
	s_or_b32 s101, s101, s2
	s_cmp_lg_u32 s100, 0
	s_cselect_b32 s101, s101, s15
	s_ashr_i32 s2, s101, 9
	s_lshl_b32 s3, s101, 3
	s_and_b32 s23, s3, 0xfe0
	s_lshl_b32 s3, s2, 12
	s_or_b32 s3, s23, s3
	v_or_b32_e32 v2, s3, v228
	s_lshl_b32 s2, s2, 1
	v_ashrrev_i32_e32 v3, 31, v2
	s_or_b32 s2, s16, s2
	v_lshlrev_b64 v[212:213], 11, v[2:3]
	s_ashr_i32 s3, s2, 31
	v_lshl_add_u64 v[2:3], v[208:209], 0, v[212:213]
	s_lshl_b64 s[2:3], s[2:3], 19
	v_sub_u32_e64 v1, s23, v226 clamp
	global_load_dwordx2 v[16:17], v0, s[4:5]
	global_load_dwordx4 v[112:115], v[2:3], off offset:512
	global_load_dwordx4 v[116:119], v[2:3], off offset:544
	global_load_dwordx4 v[120:123], v[2:3], off offset:576
	global_load_dwordx4 v[124:127], v[2:3], off offset:608
	global_load_dwordx4 v[128:131], v[2:3], off offset:640
	global_load_dwordx4 v[132:135], v[2:3], off offset:672
	global_load_dwordx4 v[136:139], v[2:3], off offset:704
	global_load_dwordx4 v[140:143], v[2:3], off offset:736
	v_lshl_add_u64 v[214:215], v[204:205], 0, s[2:3]
	v_lshlrev_b32_e32 v2, 7, v1
	v_mov_b32_e32 v3, v0
	v_lshl_add_u64 v[216:217], v[206:207], 0, s[2:3]
	v_lshl_add_u64 v[4:5], v[214:215], 0, v[2:3]
	v_lshl_add_u64 v[2:3], v[216:217], 0, v[2:3]
	global_load_dwordx4 v[144:147], v[4:5], off
	global_load_dwordx4 v[148:151], v[4:5], off offset:1024
	global_load_dwordx4 v[152:155], v[2:3], off
	global_load_dwordx4 v[156:159], v[2:3], off offset:1024
	global_load_dwordx4 v[160:163], v[4:5], off offset:2048
	global_load_dwordx4 v[164:167], v[4:5], off offset:3072
	global_load_dwordx4 v[168:171], v[2:3], off offset:2048
	global_load_dwordx4 v[172:175], v[2:3], off offset:3072
	v_mov_b32_e32 v14, v0
	v_mov_b32_e32 v15, v0
	v_mov_b32_e32 v1, v0
	v_mov_b32_e32 v2, v0
	v_mov_b32_e32 v3, v0
	v_mov_b32_e32 v4, v0
	v_mov_b32_e32 v5, v0
	v_mov_b32_e32 v6, v0
	v_mov_b32_e32 v7, v0
	v_mov_b32_e32 v8, v0
	v_mov_b32_e32 v9, v0
	s_waitcnt vmcnt(36)
	v_mov_b32_e32 v10, v0
	v_mov_b32_e32 v11, v0
	v_mov_b32_e32 v12, v0
	v_mov_b32_e32 v13, v0
	v_mov_b64_e32 v[46:47], v[14:15]
	v_mov_b64_e32 v[62:63], v[14:15]
	v_mov_b64_e32 v[78:79], v[14:15]
	s_lshl_b32 s20, s101, 3
	s_and_b32 s20, s20, 0xfe0
	s_mov_b32 s21, 0
	v_mov_b32_e32 v230, 0
	s_mov_b32 s22, -2
	v_mov_b32_e32 v233, 0
	s_addk_i32 s23, 0xff80
	v_mov_b64_e32 v[44:45], v[12:13]
	v_mov_b64_e32 v[42:43], v[10:11]
	v_mov_b64_e32 v[40:41], v[8:9]
	v_mov_b64_e32 v[38:39], v[6:7]
	v_mov_b64_e32 v[36:37], v[4:5]
	v_mov_b64_e32 v[34:35], v[2:3]
	v_mov_b64_e32 v[32:33], v[0:1]
	v_mov_b64_e32 v[60:61], v[12:13]
	v_mov_b64_e32 v[58:59], v[10:11]
	v_mov_b64_e32 v[56:57], v[8:9]
	v_mov_b64_e32 v[54:55], v[6:7]
	v_mov_b64_e32 v[52:53], v[4:5]
	v_mov_b64_e32 v[50:51], v[2:3]
	v_mov_b64_e32 v[48:49], v[0:1]
	v_mov_b64_e32 v[76:77], v[12:13]
	v_mov_b64_e32 v[74:75], v[10:11]
	v_mov_b64_e32 v[72:73], v[8:9]
	v_mov_b64_e32 v[70:71], v[6:7]
	v_mov_b64_e32 v[68:69], v[4:5]
	v_mov_b64_e32 v[66:67], v[2:3]
	v_mov_b64_e32 v[64:65], v[0:1]
	s_waitcnt vmcnt(16)
	v_mul_f32_e32 v234, 0x3fb8aa3b, v16
	v_mul_f32_e32 v231, 0x3fb8aa3b, v17
	v_mov_b64_e32 v[30:31], v[14:15]
	v_mov_b32_e32 v232, v231
	v_mov_b32_e32 v235, v234
	v_mov_b64_e32 v[28:29], v[12:13]
	v_mov_b64_e32 v[26:27], v[10:11]
	v_mov_b64_e32 v[24:25], v[8:9]
	v_mov_b64_e32 v[22:23], v[6:7]
	v_mov_b64_e32 v[20:21], v[4:5]
	v_mov_b64_e32 v[18:19], v[2:3]
	v_mov_b64_e32 v[16:17], v[0:1]
	v_mov_b32_e32 v1, v234
	v_mov_b32_e32 v236, v231
	s_branch .LBB0_560

.LBB0_650:
	v_readlane_b32 s100, v255, 40
	s_bfe_u32 s101, s93, 0x30003
	s_lshl_b32 s101, s101, 8
	s_bfe_u32 s84, s93, 0x50006
	s_lshl_b32 s84, s84, 3
	s_or_b32 s101, s101, s84
	s_and_b32 s84, s93, 7
	s_or_b32 s101, s101, s84
	s_cmp_lg_u32 s100, 0
	s_cselect_b32 s101, s101, s93
	s_bfe_u32 s84, s101, 0x60002
	v_sub_u32_e64 v1, s84, 4 clamp
	v_cmp_gt_u32_e32 vcc, 56, v1
	v_readfirstlane_b32 s85, v1
	s_min_u32 s90, s85, 56
	s_mul_i32 s85, s97, 15
	s_add_i32 s85, s85, s90
	s_sub_i32 s85, s85, s84
	s_mulk_i32 s85, 0x7c
	v_add_u32_e32 v206, s85, v205
	s_ashr_i32 s85, s101, 8
	v_cndmask_b32_e32 v2, 56, v1, vcc
	s_lshl_b32 vcc_lo, s85, 12
	s_lshl_b32 s84, s84, 6
	s_or_b32 s84, s84, vcc_lo
	v_or_b32_e32 v190, s84, v204
	v_ashrrev_i32_e32 v191, 31, v190
	v_lshlrev_b64 v[192:193], 11, v[190:191]
	s_lshl_b32 s84, s85, 2
	v_lshlrev_b32_e32 v6, 13, v2
	v_lshl_add_u64 v[2:3], v[184:185], 0, v[192:193]
	s_or_b32 s84, s84, s97
	global_load_dwordx4 v[84:87], v[2:3], off offset:1536
	global_load_dwordx4 v[88:91], v[2:3], off offset:1568
	global_load_dwordx4 v[92:95], v[2:3], off offset:1600
	global_load_dwordx4 v[96:99], v[2:3], off offset:1632
	v_add_co_u32_e32 v2, vcc, s91, v2
	s_ashr_i32 s85, s84, 31
	s_nop 0
	v_addc_co_u32_e32 v3, vcc, 0, v3, vcc
	s_lshl_b64 s[84:85], s[84:85], 19
	global_load_dwordx4 v[100:103], v[2:3], off offset:1536
	global_load_dwordx4 v[104:107], v[2:3], off offset:1568
	global_load_dwordx4 v[108:111], v[2:3], off offset:1600
	global_load_dwordx4 v[112:115], v[2:3], off offset:1632
	v_lshl_add_u64 v[2:3], v[180:181], 0, s[84:85]
	s_mov_b32 s1, s87
	s_lshl_b32 s0, s90, 13
	v_lshl_add_u64 v[4:5], v[182:183], 0, s[84:85]
	v_lshl_add_u64 v[2:3], v[2:3], 0, s[0:1]
	v_lshl_add_u64 v[4:5], v[4:5], 0, s[0:1]
	global_load_dwordx4 v[116:119], v[2:3], off
	global_load_dwordx4 v[120:123], v[4:5], off
	global_load_dwordx4 v[124:127], v[2:3], off offset:1024
	global_load_dwordx4 v[128:131], v[4:5], off offset:1024
	global_load_dwordx4 v[132:135], v[2:3], off offset:2048
	global_load_dwordx4 v[136:139], v[4:5], off offset:2048
	global_load_dwordx4 v[140:143], v[2:3], off offset:3072
	global_load_dwordx4 v[144:147], v[4:5], off offset:3072
	v_or_b32_e32 v2, s84, v6
	v_mov_b32_e32 v3, s85
	v_mov_b32_e32 v14, v0
	v_mov_b32_e32 v15, v0
	v_lshl_add_u64 v[194:195], v[188:189], 0, v[2:3]
	v_mov_b32_e32 v1, v0
	v_mov_b32_e32 v2, v0
	v_mov_b32_e32 v3, v0
	v_mov_b32_e32 v4, v0
	v_mov_b32_e32 v5, v0
	v_mov_b32_e32 v6, v0
	v_mov_b32_e32 v7, v0
	v_mov_b32_e32 v8, v0
	v_mov_b32_e32 v9, v0
	v_mov_b32_e32 v10, v0
	v_mov_b32_e32 v11, v0
	v_mov_b32_e32 v12, v0
	v_mov_b32_e32 v13, v0
	v_mov_b64_e32 v[66:67], v[14:15]
	v_mov_b64_e32 v[50:51], v[14:15]
	v_mov_b64_e32 v[34:35], v[14:15]
	v_mov_b64_e32 v[64:65], v[12:13]
	v_mov_b64_e32 v[62:63], v[10:11]
	v_mov_b64_e32 v[60:61], v[8:9]
	v_mov_b64_e32 v[58:59], v[6:7]
	v_mov_b64_e32 v[56:57], v[4:5]
	v_mov_b64_e32 v[54:55], v[2:3]
	v_mov_b64_e32 v[52:53], v[0:1]
	v_mov_b64_e32 v[48:49], v[12:13]
	v_mov_b64_e32 v[46:47], v[10:11]
	v_mov_b64_e32 v[44:45], v[8:9]
	v_mov_b64_e32 v[42:43], v[6:7]
	v_mov_b64_e32 v[40:41], v[4:5]
	v_mov_b64_e32 v[38:39], v[2:3]
	v_mov_b64_e32 v[36:37], v[0:1]
	v_mov_b64_e32 v[32:33], v[12:13]
	v_mov_b64_e32 v[30:31], v[10:11]
	v_mov_b64_e32 v[28:29], v[8:9]
	v_mov_b64_e32 v[26:27], v[6:7]
	v_mov_b64_e32 v[24:25], v[4:5]
	v_mov_b64_e32 v[22:23], v[2:3]
	v_mov_b64_e32 v[20:21], v[0:1]
	v_mov_b64_e32 v[18:19], v[14:15]
	v_mov_b32_e32 v207, 0xc6ea6000
	v_mov_b32_e32 v209, 0
	s_mov_b32 s90, -2
	v_mov_b64_e32 v[16:17], v[12:13]
	v_mov_b64_e32 v[14:15], v[10:11]
	v_mov_b64_e32 v[12:13], v[8:9]
	v_mov_b64_e32 v[10:11], v[6:7]
	v_mov_b64_e32 v[8:9], v[4:5]
	v_mov_b64_e32 v[6:7], v[2:3]
	v_mov_b64_e32 v[4:5], v[0:1]
	v_mov_b32_e32 v191, 0
	v_mov_b32_e32 v208, 0xc6ea6000
	s_branch .LBB0_652

.LBB0_742:
	s_waitcnt lgkmcnt(0)
	s_barrier
	s_waitcnt vmcnt(0)
	v_mov_b32_e32 v1, v218
	s_barrier
	s_nop 0
	v_cmp_eq_u32_e32 vcc, 0, v1
	s_and_saveexec_b64 s[2:3], vcc
	v_readlane_b32 s78, v255, 0
	v_readlane_b32 s79, v255, 1
	s_load_dwordx2 s[76:77], s[78:79], 0x100
	v_readlane_b32 s48, v255, 17
	v_readlane_b32 s97, v255, 6
	s_waitcnt lgkmcnt(0)
	v_readlane_b32 s77, v255, 7
	s_mov_b32 s69, 0x1fffe0
	s_mov_b32 s71, 0x10000
	s_mov_b32 s81, s87
	s_movk_i32 s0, 0x2000
	s_mov_b64 s[72:73], 0x40000
	s_movk_i32 s1, 0x3c0
	s_mov_b32 s74, 0x18000
	s_mov_b32 s75, 0x8000
	v_readlane_b32 s84, v255, 8
	v_readlane_b32 s85, v255, 9
	s_mov_b64 s[90:91], 0x10000
	s_mov_b32 s87, 0x40000
	s_mov_b32 s92, 0x48000
	s_mov_b32 s93, 0x50000
	v_readlane_b32 s50, v255, 19
	v_readlane_b32 s51, v255, 20
	v_readlane_b32 s49, v255, 18
	s_cbranch_execz .LBB0_794
	v_readlane_b32 s100, v255, 40
	s_nop 3
	s_cmp_eq_u32 s100, 0
	s_cbranch_scc1 .Lfb_slow_4
	v_readlane_b32 s100, v255, 41
	v_readlane_b32 s101, v255, 42
	v_mov_b32_e32 v2, 0
	v_mov_b32_e32 v3, 1
	v_mov_b32_e32 v4, 1
	s_nop 2
	global_atomic_add v3, v2, v3, s[100:101] sc0
	s_waitcnt vmcnt(0)
	v_readfirstlane_b32 vcc_hi, v3
	s_nop 3
	s_lshr_b32 vcc_lo, vcc_hi, 5
	s_add_i32 vcc_hi, vcc_hi, 1
	s_and_b32 vcc_hi, vcc_hi, 31
	s_cmp_lg_u32 vcc_hi, 0
	s_cbranch_scc1 .Lfb_spin_4
	global_atomic_add v2, v4, s[100:101] offset:128
	s_branch .Lfb_done_4

.Lfb_slow_4:
	v_mov_b32_e32 v1, s84
	s_getreg_b32 s4, hwreg(HW_REG_XCC_ID, 0, 4)
	s_waitcnt vmcnt(0) expcnt(0) lgkmcnt(0)
	ds_read_b32 v3, v1
	v_mov_b32_e32 v1, s85
	ds_read_b32 v2, v1
	s_and_b32 s46, s4, 15
	s_waitcnt lgkmcnt(1)
	v_cmp_ne_u32_e32 vcc, 0, v3
	s_cbranch_vccnz .LBB0_758
	s_add_u32 s4, s50, 0x10200
	s_addc_u32 s5, s51, 0
	s_add_u32 s6, s50, 0x10400
	s_addc_u32 s7, s51, 0
	s_add_u32 s8, s50, 0x10500
	s_addc_u32 s9, s51, 0
	s_add_u32 s10, s50, 0x10600
	s_addc_u32 s11, s51, 0
	s_add_u32 s12, s50, 0x10700
	s_addc_u32 s13, s51, 0
	s_add_u32 s14, s50, 0x10800
	s_addc_u32 s15, s51, 0
	s_add_u32 s16, s50, 0x10900
	s_addc_u32 s17, s51, 0
	s_add_u32 s18, s50, 0x10a00
	s_addc_u32 s19, s51, 0
	s_add_u32 s20, s50, 0x10b00
	s_addc_u32 s21, s51, 0
	s_add_u32 s22, s50, 0x10c00
	s_addc_u32 s23, s51, 0
	s_add_u32 s24, s50, 0x10d00
	s_addc_u32 s25, s51, 0
	s_add_u32 s26, s50, 0x10e00
	s_addc_u32 s27, s51, 0
	s_add_u32 s28, s50, 0x10f00
	s_addc_u32 s29, s51, 0
	s_add_u32 s30, s50, 0x11000
	s_addc_u32 s31, s51, 0
	s_add_u32 s34, s50, 0x11100
	s_addc_u32 s35, s51, 0
	s_add_u32 s36, s50, 0x11200
	s_addc_u32 s37, s51, 0
	s_add_u32 s38, s50, 0x11300
	s_addc_u32 s39, s51, 0
	s_mov_b32 s47, 1
	s_branch .LBB0_746
